# P4 unit prologue: the tables-ready barrier only for units with an importance pass
# speedup vs baseline: 1.0194x; 1.0194x over previous
.LBB0_605:
	s_and_b64 s[0:1], s[2:3], exec
	s_movk_i32 s0, 0xff
	v_readlane_b32 s1, v243, 48
	s_cselect_b32 s12, s0, 0x7f
	s_lshl_b32 s0, s26, 23
	s_lshl_b32 s1, s1, 19
	s_or_b32 s0, s1, s0
	s_add_u32 s11, s86, s0
	v_readlane_b32 s0, v243, 43
	v_readlane_b32 s1, v243, 44
	s_addc_u32 s19, s87, 0
	s_andn2_b64 vcc, exec, s[0:1]
	s_mov_b64 s[0:1], -1
	s_waitcnt lgkmcnt(0)
	v_readlane_b32 s6, v243, 51
	s_cmp_lt_i32 s6, 4
	s_cbranch_scc1 .Lnb_skip
	s_and_b64 s[6:7], s[2:3], exec
	s_cbranch_scc0 .Lnb_skip
	s_barrier
.Lnb_skip:
	s_cbranch_vccnz .LBB0_607
	v_readlane_b32 s0, v243, 47
	s_addk_i32 s0, 0xff80
	s_ashr_i32 s0, s0, 6
	v_readlane_b32 s1, v243, 51
	s_cmp_gt_i32 s1, 0
	s_cselect_b32 s10, s0, 0
	s_add_u32 s6, s11, 0x4000000
	s_addc_u32 s7, s19, 0
	s_add_u32 s8, s11, 0x5000000
	s_addc_u32 s9, s19, 0
	s_mov_b64 s[0:1], 0
